# mla_sample_combine: 32 page-group partial loads issued together (one wait) instead of 32 serialized round trips; same fma order
# baseline (speedup 1.0000x reference)
.LBB0_1945:
	s_or_b64 exec, exec, s[38:39]
	v_add_f32_e32 v5, v21, v24
	v_max3_f32 v0, v0, v26, v5
	v_add_f32_e32 v81, v25, v28
	v_max_f32_e32 v4, v0, v81
	v_cndmask_b32_e64 v0, v4, v0, s[2:3]
	s_waitcnt lgkmcnt(0)
	v_add_f32_e32 v78, v30, v32
	v_max_f32_e32 v4, v0, v78
	v_cndmask_b32_e64 v0, v4, v0, s[4:5]
	s_lshl_b32 s28, s37, 10
	v_add_f32_dpp v4, v20, v20 quad_perm:[1,0,3,2] row_mask:0xf bank_mask:0xf bound_ctrl:1
	s_ashr_i32 s37, s36, 31
	s_lshl_b64 s[38:39], s[36:37], 15
	v_add_f32_dpp v4, v4, v4 quad_perm:[2,3,0,1] row_mask:0xf bank_mask:0xf bound_ctrl:1
	s_ashr_i32 s35, s34, 31
	s_lshl_b64 s[34:35], s[34:35], 12
	v_add_f32_dpp v4, v4, v4 row_half_mirror row_mask:0xf bank_mask:0xf bound_ctrl:1
	s_andn2_b64 vcc, exec, s[18:19]
	s_nop 0
	v_add_f32_dpp v4, v4, v4 row_mirror row_mask:0xf bank_mask:0xf bound_ctrl:1
	ds_bpermute_b32 v20, v9, v4
	s_waitcnt lgkmcnt(0)
	v_add_f32_e32 v4, v4, v20
	ds_bpermute_b32 v20, v76, v4
	s_waitcnt lgkmcnt(0)
	v_add_f32_e32 v79, v4, v20
	v_max_f32_e32 v80, v0, v79
	v_cndmask_b32_e64 v82, v0, v80, s[6:7]
	v_sub_f32_e32 v0, v2, v82
	v_exp_f32_e32 v0, v0
	ds_bpermute_b32 v88, v7, v0
	v_mul_f32_e32 v2, v3, v0
	ds_bpermute_b32 v90, v27, v0
	ds_bpermute_b32 v92, v29, v0
	v_mov_b32_dpp v2, v2 quad_perm:[1,0,3,2] row_mask:0xf bank_mask:0xf bound_ctrl:1
	v_fmac_f32_e32 v2, v3, v0
	ds_bpermute_b32 v94, v31, v0
	ds_bpermute_b32 v96, v33, v0
	v_add_f32_dpp v2, v2, v2 quad_perm:[2,3,0,1] row_mask:0xf bank_mask:0xf bound_ctrl:1
	ds_bpermute_b32 v98, v35, v0
	ds_bpermute_b32 v100, v37, v0
	v_add_f32_dpp v2, v2, v2 row_half_mirror row_mask:0xf bank_mask:0xf bound_ctrl:1
	ds_bpermute_b32 v102, v39, v0
	ds_bpermute_b32 v62, v41, v0
	v_add_f32_dpp v2, v2, v2 row_mirror row_mask:0xf bank_mask:0xf bound_ctrl:1
	ds_bpermute_b32 v3, v9, v2
	ds_bpermute_b32 v60, v43, v0
	ds_bpermute_b32 v58, v45, v0
	ds_bpermute_b32 v56, v47, v0
	ds_bpermute_b32 v54, v49, v0
	s_waitcnt lgkmcnt(4)
	v_add_f32_e32 v3, v2, v3
	ds_bpermute_b32 v20, v76, v3
	ds_bpermute_b32 v52, v51, v0
	ds_bpermute_b32 v50, v53, v0
	ds_bpermute_b32 v48, v55, v0
	ds_bpermute_b32 v46, v57, v0
	s_waitcnt lgkmcnt(4)
	v_add_f32_e32 v3, v3, v20
	v_lshl_add_u64 v[20:21], v[10:11], 0, s[28:29]
	ds_bpermute_b32 v44, v59, v0
	ds_bpermute_b32 v42, v61, v0
	ds_bpermute_b32 v40, v63, v0
	ds_bpermute_b32 v38, v64, v0
	ds_bpermute_b32 v36, v65, v0
	ds_bpermute_b32 v34, v66, v0
	ds_bpermute_b32 v32, v67, v0
	ds_bpermute_b32 v30, v68, v0
	ds_bpermute_b32 v28, v69, v0
	ds_bpermute_b32 v26, v70, v0
	ds_bpermute_b32 v24, v71, v0
	ds_bpermute_b32 v22, v72, v0
	ds_bpermute_b32 v4, v73, v0
	ds_bpermute_b32 v2, v74, v0
	ds_bpermute_b32 v0, v75, v0
	s_mov_b32 s100, s36
	s_ashr_i32 s101, s100, 31
	s_lshl_b64 s[100:101], s[100:101], 15
	v_lshl_add_u64 v[246:247], v[20:21], 0, s[100:101]
	global_load_dwordx4 v[106:109], v[246:247], off
	s_or_b32 s100, s36, 1
	s_ashr_i32 s101, s100, 31
	s_lshl_b64 s[100:101], s[100:101], 15
	v_lshl_add_u64 v[246:247], v[20:21], 0, s[100:101]
	global_load_dwordx4 v[110:113], v[246:247], off
	s_or_b32 s100, s36, 2
	s_ashr_i32 s101, s100, 31
	s_lshl_b64 s[100:101], s[100:101], 15
	v_lshl_add_u64 v[246:247], v[20:21], 0, s[100:101]
	global_load_dwordx4 v[114:117], v[246:247], off
	s_or_b32 s100, s36, 3
	s_ashr_i32 s101, s100, 31
	s_lshl_b64 s[100:101], s[100:101], 15
	v_lshl_add_u64 v[246:247], v[20:21], 0, s[100:101]
	global_load_dwordx4 v[118:121], v[246:247], off
	s_or_b32 s100, s36, 4
	s_ashr_i32 s101, s100, 31
	s_lshl_b64 s[100:101], s[100:101], 15
	v_lshl_add_u64 v[246:247], v[20:21], 0, s[100:101]
	global_load_dwordx4 v[122:125], v[246:247], off
	s_or_b32 s100, s36, 5
	s_ashr_i32 s101, s100, 31
	s_lshl_b64 s[100:101], s[100:101], 15
	v_lshl_add_u64 v[246:247], v[20:21], 0, s[100:101]
	global_load_dwordx4 v[126:129], v[246:247], off
	s_or_b32 s100, s36, 6
	s_ashr_i32 s101, s100, 31
	s_lshl_b64 s[100:101], s[100:101], 15
	v_lshl_add_u64 v[246:247], v[20:21], 0, s[100:101]
	global_load_dwordx4 v[130:133], v[246:247], off
	s_or_b32 s100, s36, 7
	s_ashr_i32 s101, s100, 31
	s_lshl_b64 s[100:101], s[100:101], 15
	v_lshl_add_u64 v[246:247], v[20:21], 0, s[100:101]
	global_load_dwordx4 v[134:137], v[246:247], off
	s_or_b32 s100, s36, 8
	s_ashr_i32 s101, s100, 31
	s_lshl_b64 s[100:101], s[100:101], 15
	v_lshl_add_u64 v[246:247], v[20:21], 0, s[100:101]
	global_load_dwordx4 v[138:141], v[246:247], off
	s_or_b32 s100, s36, 9
	s_ashr_i32 s101, s100, 31
	s_lshl_b64 s[100:101], s[100:101], 15
	v_lshl_add_u64 v[246:247], v[20:21], 0, s[100:101]
	global_load_dwordx4 v[142:145], v[246:247], off
	s_or_b32 s100, s36, 10
	s_ashr_i32 s101, s100, 31
	s_lshl_b64 s[100:101], s[100:101], 15
	v_lshl_add_u64 v[246:247], v[20:21], 0, s[100:101]
	global_load_dwordx4 v[146:149], v[246:247], off
	s_or_b32 s100, s36, 11
	s_ashr_i32 s101, s100, 31
	s_lshl_b64 s[100:101], s[100:101], 15
	v_lshl_add_u64 v[246:247], v[20:21], 0, s[100:101]
	global_load_dwordx4 v[150:153], v[246:247], off
	s_or_b32 s100, s36, 12
	s_ashr_i32 s101, s100, 31
	s_lshl_b64 s[100:101], s[100:101], 15
	v_lshl_add_u64 v[246:247], v[20:21], 0, s[100:101]
	global_load_dwordx4 v[154:157], v[246:247], off
	s_or_b32 s100, s36, 13
	s_ashr_i32 s101, s100, 31
	s_lshl_b64 s[100:101], s[100:101], 15
	v_lshl_add_u64 v[246:247], v[20:21], 0, s[100:101]
	global_load_dwordx4 v[158:161], v[246:247], off
	s_or_b32 s100, s36, 14
	s_ashr_i32 s101, s100, 31
	s_lshl_b64 s[100:101], s[100:101], 15
	v_lshl_add_u64 v[246:247], v[20:21], 0, s[100:101]
	global_load_dwordx4 v[162:165], v[246:247], off
	s_or_b32 s100, s36, 15
	s_ashr_i32 s101, s100, 31
	s_lshl_b64 s[100:101], s[100:101], 15
	v_lshl_add_u64 v[246:247], v[20:21], 0, s[100:101]
	global_load_dwordx4 v[166:169], v[246:247], off
	s_or_b32 s100, s36, 16
	s_ashr_i32 s101, s100, 31
	s_lshl_b64 s[100:101], s[100:101], 15
	v_lshl_add_u64 v[246:247], v[20:21], 0, s[100:101]
	global_load_dwordx4 v[170:173], v[246:247], off
	s_or_b32 s100, s36, 17
	s_ashr_i32 s101, s100, 31
	s_lshl_b64 s[100:101], s[100:101], 15
	v_lshl_add_u64 v[246:247], v[20:21], 0, s[100:101]
	global_load_dwordx4 v[174:177], v[246:247], off
	s_or_b32 s100, s36, 18
	s_ashr_i32 s101, s100, 31
	s_lshl_b64 s[100:101], s[100:101], 15
	v_lshl_add_u64 v[246:247], v[20:21], 0, s[100:101]
	global_load_dwordx4 v[178:181], v[246:247], off
	s_or_b32 s100, s36, 19
	s_ashr_i32 s101, s100, 31
	s_lshl_b64 s[100:101], s[100:101], 15
	v_lshl_add_u64 v[246:247], v[20:21], 0, s[100:101]
	global_load_dwordx4 v[182:185], v[246:247], off
	s_or_b32 s100, s36, 20
	s_ashr_i32 s101, s100, 31
	s_lshl_b64 s[100:101], s[100:101], 15
	v_lshl_add_u64 v[246:247], v[20:21], 0, s[100:101]
	global_load_dwordx4 v[186:189], v[246:247], off
	s_or_b32 s100, s36, 21
	s_ashr_i32 s101, s100, 31
	s_lshl_b64 s[100:101], s[100:101], 15
	v_lshl_add_u64 v[246:247], v[20:21], 0, s[100:101]
	global_load_dwordx4 v[190:193], v[246:247], off
	s_or_b32 s100, s36, 22
	s_ashr_i32 s101, s100, 31
	s_lshl_b64 s[100:101], s[100:101], 15
	v_lshl_add_u64 v[246:247], v[20:21], 0, s[100:101]
	global_load_dwordx4 v[194:197], v[246:247], off
	s_or_b32 s100, s36, 23
	s_ashr_i32 s101, s100, 31
	s_lshl_b64 s[100:101], s[100:101], 15
	v_lshl_add_u64 v[246:247], v[20:21], 0, s[100:101]
	global_load_dwordx4 v[198:201], v[246:247], off
	s_or_b32 s100, s36, 24
	s_ashr_i32 s101, s100, 31
	s_lshl_b64 s[100:101], s[100:101], 15
	v_lshl_add_u64 v[246:247], v[20:21], 0, s[100:101]
	global_load_dwordx4 v[202:205], v[246:247], off
	s_or_b32 s100, s36, 25
	s_ashr_i32 s101, s100, 31
	s_lshl_b64 s[100:101], s[100:101], 15
	v_lshl_add_u64 v[246:247], v[20:21], 0, s[100:101]
	global_load_dwordx4 v[206:209], v[246:247], off
	s_or_b32 s100, s36, 26
	s_ashr_i32 s101, s100, 31
	s_lshl_b64 s[100:101], s[100:101], 15
	v_lshl_add_u64 v[246:247], v[20:21], 0, s[100:101]
	global_load_dwordx4 v[210:213], v[246:247], off
	s_or_b32 s100, s36, 27
	s_ashr_i32 s101, s100, 31
	s_lshl_b64 s[100:101], s[100:101], 15
	v_lshl_add_u64 v[246:247], v[20:21], 0, s[100:101]
	global_load_dwordx4 v[214:217], v[246:247], off
	s_or_b32 s100, s36, 28
	s_ashr_i32 s101, s100, 31
	s_lshl_b64 s[100:101], s[100:101], 15
	v_lshl_add_u64 v[246:247], v[20:21], 0, s[100:101]
	global_load_dwordx4 v[218:221], v[246:247], off
	s_or_b32 s100, s36, 29
	s_ashr_i32 s101, s100, 31
	s_lshl_b64 s[100:101], s[100:101], 15
	v_lshl_add_u64 v[246:247], v[20:21], 0, s[100:101]
	global_load_dwordx4 v[222:225], v[246:247], off
	s_or_b32 s100, s36, 30
	s_ashr_i32 s101, s100, 31
	s_lshl_b64 s[100:101], s[100:101], 15
	v_lshl_add_u64 v[246:247], v[20:21], 0, s[100:101]
	global_load_dwordx4 v[238:241], v[246:247], off
	s_or_b32 s100, s40, 31
	s_ashr_i32 s101, s100, 31
	s_lshl_b64 s[100:101], s[100:101], 15
	v_lshl_add_u64 v[246:247], v[20:21], 0, s[100:101]
	global_load_dwordx4 v[242:245], v[246:247], off
	s_waitcnt vmcnt(0) lgkmcnt(0)
	v_lshl_add_u64 v[20:21], v[16:17], 0, s[34:35]
	v_pk_fma_f32 v[104:105], v[88:89], v[108:109], 0 op_sel_hi:[0,1,0]
	v_pk_fma_f32 v[88:89], v[88:89], v[106:107], 0 op_sel_hi:[0,1,0]
	v_pk_fma_f32 v[88:89], v[90:91], v[110:111], v[88:89] op_sel_hi:[0,1,1]
	v_pk_fma_f32 v[90:91], v[90:91], v[112:113], v[104:105] op_sel_hi:[0,1,1]
	v_pk_fma_f32 v[88:89], v[92:93], v[114:115], v[88:89] op_sel_hi:[0,1,1]
	v_pk_fma_f32 v[90:91], v[92:93], v[116:117], v[90:91] op_sel_hi:[0,1,1]
	v_pk_fma_f32 v[88:89], v[94:95], v[118:119], v[88:89] op_sel_hi:[0,1,1]
	v_pk_fma_f32 v[90:91], v[94:95], v[120:121], v[90:91] op_sel_hi:[0,1,1]
	v_pk_fma_f32 v[88:89], v[96:97], v[122:123], v[88:89] op_sel_hi:[0,1,1]
	v_pk_fma_f32 v[90:91], v[96:97], v[124:125], v[90:91] op_sel_hi:[0,1,1]
	v_pk_fma_f32 v[88:89], v[98:99], v[126:127], v[88:89] op_sel_hi:[0,1,1]
	v_pk_fma_f32 v[90:91], v[98:99], v[128:129], v[90:91] op_sel_hi:[0,1,1]
	v_pk_fma_f32 v[88:89], v[100:101], v[130:131], v[88:89] op_sel_hi:[0,1,1]
	v_pk_fma_f32 v[90:91], v[100:101], v[132:133], v[90:91] op_sel_hi:[0,1,1]
	v_pk_fma_f32 v[88:89], v[102:103], v[134:135], v[88:89] op_sel_hi:[0,1,1]
	v_pk_fma_f32 v[90:91], v[102:103], v[136:137], v[90:91] op_sel_hi:[0,1,1]
	v_pk_fma_f32 v[88:89], v[62:63], v[138:139], v[88:89] op_sel_hi:[0,1,1]
	v_pk_fma_f32 v[90:91], v[62:63], v[140:141], v[90:91] op_sel_hi:[0,1,1]
	v_pk_fma_f32 v[88:89], v[60:61], v[142:143], v[88:89] op_sel_hi:[0,1,1]
	v_pk_fma_f32 v[90:91], v[60:61], v[144:145], v[90:91] op_sel_hi:[0,1,1]
	v_pk_fma_f32 v[88:89], v[58:59], v[146:147], v[88:89] op_sel_hi:[0,1,1]
	v_pk_fma_f32 v[90:91], v[58:59], v[148:149], v[90:91] op_sel_hi:[0,1,1]
	v_pk_fma_f32 v[88:89], v[56:57], v[150:151], v[88:89] op_sel_hi:[0,1,1]
	v_pk_fma_f32 v[90:91], v[56:57], v[152:153], v[90:91] op_sel_hi:[0,1,1]
	v_pk_fma_f32 v[88:89], v[54:55], v[154:155], v[88:89] op_sel_hi:[0,1,1]
	v_pk_fma_f32 v[90:91], v[54:55], v[156:157], v[90:91] op_sel_hi:[0,1,1]
	v_pk_fma_f32 v[88:89], v[52:53], v[158:159], v[88:89] op_sel_hi:[0,1,1]
	v_pk_fma_f32 v[90:91], v[52:53], v[160:161], v[90:91] op_sel_hi:[0,1,1]
	v_pk_fma_f32 v[88:89], v[50:51], v[162:163], v[88:89] op_sel_hi:[0,1,1]
	v_pk_fma_f32 v[90:91], v[50:51], v[164:165], v[90:91] op_sel_hi:[0,1,1]
	v_pk_fma_f32 v[88:89], v[48:49], v[166:167], v[88:89] op_sel_hi:[0,1,1]
	v_pk_fma_f32 v[90:91], v[48:49], v[168:169], v[90:91] op_sel_hi:[0,1,1]
	v_pk_fma_f32 v[88:89], v[46:47], v[170:171], v[88:89] op_sel_hi:[0,1,1]
	v_pk_fma_f32 v[90:91], v[46:47], v[172:173], v[90:91] op_sel_hi:[0,1,1]
	v_pk_fma_f32 v[88:89], v[44:45], v[174:175], v[88:89] op_sel_hi:[0,1,1]
	v_pk_fma_f32 v[90:91], v[44:45], v[176:177], v[90:91] op_sel_hi:[0,1,1]
	v_pk_fma_f32 v[88:89], v[42:43], v[178:179], v[88:89] op_sel_hi:[0,1,1]
	v_pk_fma_f32 v[90:91], v[42:43], v[180:181], v[90:91] op_sel_hi:[0,1,1]
	v_pk_fma_f32 v[88:89], v[40:41], v[182:183], v[88:89] op_sel_hi:[0,1,1]
	v_pk_fma_f32 v[90:91], v[40:41], v[184:185], v[90:91] op_sel_hi:[0,1,1]
	v_pk_fma_f32 v[88:89], v[38:39], v[186:187], v[88:89] op_sel_hi:[0,1,1]
	v_pk_fma_f32 v[90:91], v[38:39], v[188:189], v[90:91] op_sel_hi:[0,1,1]
	v_pk_fma_f32 v[88:89], v[36:37], v[190:191], v[88:89] op_sel_hi:[0,1,1]
	v_pk_fma_f32 v[90:91], v[36:37], v[192:193], v[90:91] op_sel_hi:[0,1,1]
	v_pk_fma_f32 v[88:89], v[34:35], v[194:195], v[88:89] op_sel_hi:[0,1,1]
	v_pk_fma_f32 v[90:91], v[34:35], v[196:197], v[90:91] op_sel_hi:[0,1,1]
	v_pk_fma_f32 v[88:89], v[32:33], v[198:199], v[88:89] op_sel_hi:[0,1,1]
	v_pk_fma_f32 v[90:91], v[32:33], v[200:201], v[90:91] op_sel_hi:[0,1,1]
	v_pk_fma_f32 v[88:89], v[30:31], v[202:203], v[88:89] op_sel_hi:[0,1,1]
	v_pk_fma_f32 v[90:91], v[30:31], v[204:205], v[90:91] op_sel_hi:[0,1,1]
	v_pk_fma_f32 v[88:89], v[28:29], v[206:207], v[88:89] op_sel_hi:[0,1,1]
	v_pk_fma_f32 v[90:91], v[28:29], v[208:209], v[90:91] op_sel_hi:[0,1,1]
	v_pk_fma_f32 v[88:89], v[26:27], v[210:211], v[88:89] op_sel_hi:[0,1,1]
	v_pk_fma_f32 v[90:91], v[26:27], v[212:213], v[90:91] op_sel_hi:[0,1,1]
	v_pk_fma_f32 v[88:89], v[24:25], v[214:215], v[88:89] op_sel_hi:[0,1,1]
	v_pk_fma_f32 v[24:25], v[24:25], v[216:217], v[90:91] op_sel_hi:[0,1,1]
	v_pk_fma_f32 v[86:87], v[22:23], v[220:221], v[24:25] op_sel_hi:[0,1,1]
	v_pk_fma_f32 v[84:85], v[22:23], v[218:219], v[88:89] op_sel_hi:[0,1,1]
	v_pk_fma_f32 v[84:85], v[4:5], v[222:223], v[84:85] op_sel_hi:[0,1,1]
	v_pk_fma_f32 v[86:87], v[4:5], v[224:225], v[86:87] op_sel_hi:[0,1,1]
	v_pk_fma_f32 v[86:87], v[2:3], v[240:241], v[86:87] op_sel_hi:[0,1,1]
	v_pk_fma_f32 v[84:85], v[2:3], v[238:239], v[84:85] op_sel_hi:[0,1,1]
	v_pk_fma_f32 v[22:23], v[0:1], v[242:243], v[84:85] op_sel_hi:[0,1,1]
	v_pk_fma_f32 v[24:25], v[0:1], v[244:245], v[86:87] op_sel_hi:[0,1,1]
	v_sub_f32_e32 v0, v5, v82
	v_exp_f32_e32 v0, v0
	s_nop 0
	v_add_f32_e32 v26, v0, v3
	global_load_dwordx4 v[2:5], v[20:21], off
	s_waitcnt vmcnt(0)
	v_pk_fma_f32 v[4:5], v[0:1], v[4:5], v[24:25] op_sel_hi:[0,1,1]
	v_pk_fma_f32 v[2:3], v[0:1], v[2:3], v[22:23] op_sel_hi:[0,1,1]
	s_cbranch_vccz .LBB0_1952
	s_andn2_b64 vcc, exec, s[20:21]
	s_cbranch_vccz .LBB0_1953
